# P1 main K-loop: LDS-DMA loads addressed as SGPR base + 32-bit lane offset instead of per-load 64-bit VGPR addresses (14 VALU fewer per two K-tiles)
# speedup vs baseline: 1.0047x; 1.0032x over previous
.LBB0_107:
	ds_read_b128 v[150:153], v248
	ds_read_b128 v[154:157], v248 offset:1024
	ds_read_b128 v[158:161], v248 offset:2048
	ds_read_b128 v[162:165], v248 offset:3072
	ds_read_b128 v[134:137], v249
	ds_read_b128 v[138:141], v249 offset:1024
	ds_read_b128 v[142:145], v249 offset:2048
	ds_read_b128 v[146:149], v249 offset:3072
	s_mov_b64 s[0:1], s[76:77]
	s_add_u32 s76, s0, 0x100
	s_addc_u32 s77, s1, 0
	s_cmp_lg_u32 s45, 12
	s_cselect_b64 s[88:89], -1, 0
	s_and_b64 s[2:3], s[88:89], exec
	s_cselect_b32 s3, s44, s63
	s_cselect_b32 s2, s36, s65
	s_cselect_b32 s85, s77, s4
	s_cselect_b32 s84, s76, s43
	s_add_i32 m0, s61, 0xc000
	s_waitcnt lgkmcnt(0)
	ds_read_b128 v[166:169], v250
	ds_read_b128 v[170:173], v250 offset:1024
	ds_read_b128 v[174:177], v250 offset:2048
	ds_read_b128 v[178:181], v250 offset:3072
	ds_read_b128 v[182:185], v250 offset:4096
	ds_read_b128 v[186:189], v250 offset:5120
	ds_read_b128 v[190:193], v250 offset:6144
	ds_read_b128 v[194:197], v250 offset:7168
	global_load_lds_dwordx4 v214, s[0:1]
	s_add_i32 m0, s61, 0xe000
	s_nop 0
	global_load_lds_dwordx4 v216, s[0:1]
	s_waitcnt vmcnt(8)
	s_waitcnt lgkmcnt(0)
	s_setprio 1
	s_barrier
	v_mfma_f32_16x16x32_bf16 v[102:105], v[150:153], v[166:169], v[102:105]
	v_mfma_f32_16x16x32_bf16 v[70:73], v[158:161], v[166:169], v[70:73]
	v_mfma_f32_16x16x32_bf16 v[114:117], v[150:153], v[174:177], v[114:117]
	v_mfma_f32_16x16x32_bf16 v[82:85], v[158:161], v[174:177], v[82:85]
	v_mfma_f32_16x16x32_bf16 v[110:113], v[150:153], v[182:185], v[110:113]
	v_mfma_f32_16x16x32_bf16 v[78:81], v[158:161], v[182:185], v[78:81]
	v_mfma_f32_16x16x32_bf16 v[106:109], v[150:153], v[190:193], v[106:109]
	v_mfma_f32_16x16x32_bf16 v[74:77], v[158:161], v[190:193], v[74:77]
	v_mfma_f32_16x16x32_bf16 v[102:105], v[154:157], v[170:173], v[102:105]
	v_mfma_f32_16x16x32_bf16 v[70:73], v[162:165], v[170:173], v[70:73]
	v_mfma_f32_16x16x32_bf16 v[114:117], v[154:157], v[178:181], v[114:117]
	v_mfma_f32_16x16x32_bf16 v[82:85], v[162:165], v[178:181], v[82:85]
	v_mfma_f32_16x16x32_bf16 v[110:113], v[154:157], v[186:189], v[110:113]
	v_mfma_f32_16x16x32_bf16 v[78:81], v[162:165], v[186:189], v[78:81]
	v_mfma_f32_16x16x32_bf16 v[106:109], v[154:157], v[194:197], v[106:109]
	v_mfma_f32_16x16x32_bf16 v[74:77], v[162:165], v[194:197], v[74:77]
	v_mfma_f32_16x16x32_bf16 v[130:133], v[134:137], v[166:169], v[130:133]
	v_mfma_f32_16x16x32_bf16 v[98:101], v[142:145], v[166:169], v[98:101]
	v_mfma_f32_16x16x32_bf16 v[126:129], v[134:137], v[174:177], v[126:129]
	v_mfma_f32_16x16x32_bf16 v[94:97], v[142:145], v[174:177], v[94:97]
	v_mfma_f32_16x16x32_bf16 v[122:125], v[134:137], v[182:185], v[122:125]
	v_mfma_f32_16x16x32_bf16 v[90:93], v[142:145], v[182:185], v[90:93]
	v_mfma_f32_16x16x32_bf16 v[118:121], v[134:137], v[190:193], v[118:121]
	v_mfma_f32_16x16x32_bf16 v[86:89], v[142:145], v[190:193], v[86:89]
	v_mfma_f32_16x16x32_bf16 v[130:133], v[138:141], v[170:173], v[130:133]
	v_mfma_f32_16x16x32_bf16 v[98:101], v[146:149], v[170:173], v[98:101]
	v_mfma_f32_16x16x32_bf16 v[126:129], v[138:141], v[178:181], v[126:129]
	v_mfma_f32_16x16x32_bf16 v[94:97], v[146:149], v[178:181], v[94:97]
	v_mfma_f32_16x16x32_bf16 v[122:125], v[138:141], v[186:189], v[122:125]
	v_mfma_f32_16x16x32_bf16 v[90:93], v[146:149], v[186:189], v[90:93]
	v_mfma_f32_16x16x32_bf16 v[118:121], v[138:141], v[194:197], v[118:121]
	v_mfma_f32_16x16x32_bf16 v[86:89], v[146:149], v[194:197], v[86:89]
	s_setprio 0
	s_barrier
	ds_read_b128 v[190:193], v250 offset:16384
	ds_read_b128 v[194:197], v250 offset:17408
	ds_read_b128 v[182:185], v250 offset:18432
	ds_read_b128 v[186:189], v250 offset:19456
	ds_read_b128 v[174:177], v250 offset:20480
	ds_read_b128 v[178:181], v250 offset:21504
	ds_read_b128 v[166:169], v250 offset:22528
	ds_read_b128 v[170:173], v250 offset:23552
	s_mov_b32 m0, s73
	s_add_u32 s0, s2, 0x40000
	global_load_lds_dwordx4 v208, s[2:3]
	s_mov_b32 m0, s75
	s_addc_u32 s1, s3, 0
	global_load_lds_dwordx4 v212, s[2:3]
	s_mov_b32 m0, s92
	s_nop 0
	global_load_lds_dwordx4 v208, s[0:1]
	s_mov_b32 m0, s93
	s_nop 0
	global_load_lds_dwordx4 v212, s[0:1]
	s_mov_b32 m0, s61
	s_nop 0
	global_load_lds_dwordx4 v206, s[84:85]
	s_mov_b32 m0, s94
	s_nop 0
	global_load_lds_dwordx4 v210, s[84:85]
	s_waitcnt vmcnt(8)

.LBB0_113:
	s_barrier
	v_add_u32_e32 v3, 0x18000, v247
	ds_read_b128 v[150:153], v3
	ds_read_b128 v[154:157], v3 offset:1024
	ds_read_b128 v[158:161], v3 offset:2048
	ds_read_b128 v[162:165], v3 offset:3072
	v_add_u32_e32 v3, 0x1c000, v247
	ds_read_b128 v[134:137], v3
	ds_read_b128 v[138:141], v3 offset:1024
	ds_read_b128 v[142:145], v3 offset:2048
	ds_read_b128 v[146:149], v3 offset:3072
	s_waitcnt lgkmcnt(0)
	ds_read_b128 v[190:193], v250 offset:32768
	ds_read_b128 v[194:197], v250 offset:33792
	ds_read_b128 v[182:185], v250 offset:34816
	ds_read_b128 v[186:189], v250 offset:35840
	ds_read_b128 v[174:177], v250 offset:36864
	ds_read_b128 v[178:181], v250 offset:37888
	ds_read_b128 v[166:169], v250 offset:38912
	ds_read_b128 v[170:173], v250 offset:39936
	s_add_u32 s84, s84, 0x40000
	s_addc_u32 s85, s85, 0
	s_mov_b32 m0, s95
	s_nop 0
	global_load_lds_dwordx4 v206, s[84:85]
	s_mov_b32 m0, s96
	s_nop 0
	global_load_lds_dwordx4 v210, s[84:85]
	s_waitcnt vmcnt(8)
.LBB0_117:
	s_waitcnt lgkmcnt(0)
	s_setprio 1
	s_barrier
	v_mfma_f32_16x16x32_bf16 v[102:105], v[150:153], v[190:193], v[102:105]
	v_mfma_f32_16x16x32_bf16 v[70:73], v[158:161], v[190:193], v[70:73]
	v_mfma_f32_16x16x32_bf16 v[114:117], v[150:153], v[182:185], v[114:117]
	v_mfma_f32_16x16x32_bf16 v[82:85], v[158:161], v[182:185], v[82:85]
	v_mfma_f32_16x16x32_bf16 v[110:113], v[150:153], v[174:177], v[110:113]
	v_mfma_f32_16x16x32_bf16 v[78:81], v[158:161], v[174:177], v[78:81]
	v_mfma_f32_16x16x32_bf16 v[106:109], v[150:153], v[166:169], v[106:109]
	v_mfma_f32_16x16x32_bf16 v[74:77], v[158:161], v[166:169], v[74:77]
	v_mfma_f32_16x16x32_bf16 v[102:105], v[154:157], v[194:197], v[102:105]
	v_mfma_f32_16x16x32_bf16 v[70:73], v[162:165], v[194:197], v[70:73]
	v_mfma_f32_16x16x32_bf16 v[114:117], v[154:157], v[186:189], v[114:117]
	v_mfma_f32_16x16x32_bf16 v[82:85], v[162:165], v[186:189], v[82:85]
	v_mfma_f32_16x16x32_bf16 v[110:113], v[154:157], v[178:181], v[110:113]
	v_mfma_f32_16x16x32_bf16 v[78:81], v[162:165], v[178:181], v[78:81]
	v_mfma_f32_16x16x32_bf16 v[106:109], v[154:157], v[170:173], v[106:109]
	v_mfma_f32_16x16x32_bf16 v[74:77], v[162:165], v[170:173], v[74:77]
	v_mfma_f32_16x16x32_bf16 v[130:133], v[134:137], v[190:193], v[130:133]
	v_mfma_f32_16x16x32_bf16 v[98:101], v[142:145], v[190:193], v[98:101]
	v_mfma_f32_16x16x32_bf16 v[126:129], v[134:137], v[182:185], v[126:129]
	v_mfma_f32_16x16x32_bf16 v[94:97], v[142:145], v[182:185], v[94:97]
	v_mfma_f32_16x16x32_bf16 v[122:125], v[134:137], v[174:177], v[122:125]
	v_mfma_f32_16x16x32_bf16 v[90:93], v[142:145], v[174:177], v[90:93]
	v_mfma_f32_16x16x32_bf16 v[118:121], v[134:137], v[166:169], v[118:121]
	v_mfma_f32_16x16x32_bf16 v[86:89], v[142:145], v[166:169], v[86:89]
	v_mfma_f32_16x16x32_bf16 v[130:133], v[138:141], v[194:197], v[130:133]
	v_mfma_f32_16x16x32_bf16 v[98:101], v[146:149], v[194:197], v[98:101]
	v_mfma_f32_16x16x32_bf16 v[126:129], v[138:141], v[186:189], v[126:129]
	v_mfma_f32_16x16x32_bf16 v[94:97], v[146:149], v[186:189], v[94:97]
	v_mfma_f32_16x16x32_bf16 v[122:125], v[138:141], v[178:181], v[122:125]
	v_mfma_f32_16x16x32_bf16 v[90:93], v[146:149], v[178:181], v[90:93]
	v_mfma_f32_16x16x32_bf16 v[118:121], v[138:141], v[170:173], v[118:121]
	v_mfma_f32_16x16x32_bf16 v[86:89], v[146:149], v[170:173], v[86:89]
	s_setprio 0
	s_barrier
	ds_read_b128 v[190:193], v250 offset:49152
	ds_read_b128 v[194:197], v250 offset:50176
	ds_read_b128 v[182:185], v250 offset:51200
	ds_read_b128 v[186:189], v250 offset:52224
	ds_read_b128 v[174:177], v250 offset:53248
	ds_read_b128 v[178:181], v250 offset:54272
	ds_read_b128 v[166:169], v250 offset:55296
	ds_read_b128 v[170:173], v250 offset:56320
	s_add_u32 s2, s2, 0x80
	s_addc_u32 s3, s3, 0
	s_mov_b32 m0, s54
	s_add_u32 s0, s2, 0x40000
	global_load_lds_dwordx4 v208, s[2:3]
	s_mov_b32 m0, s55
	s_addc_u32 s1, s3, 0
	global_load_lds_dwordx4 v212, s[2:3]
	s_mov_b32 m0, s59
	s_sub_u32 s84, s84, 0x3ff80
	global_load_lds_dwordx4 v208, s[0:1]
	s_mov_b32 m0, s24
	s_subb_u32 s85, s85, 0
	global_load_lds_dwordx4 v212, s[0:1]
	s_mov_b32 m0, s57
	s_nop 0
	global_load_lds_dwordx4 v206, s[84:85]
	s_mov_b32 m0, s58
	s_nop 0
	global_load_lds_dwordx4 v210, s[84:85]
	s_waitcnt vmcnt(8)
